# replace cooperative-groups grid sync after prologue with the XCD-hierarchical barrier (route through loop-bottom instance)
# baseline (speedup 1.0000x reference)
; __device__ __forceinline__ unsigned xb_ld(unsigned* p)              { return __hip_atomic_load(p, __ATOMIC_RELAXED, __HIP_MEMORY_SCOPE_AGENT); }
; __device__ __forceinline__ void xcd_barrier_complete(unsigned* bar, unsigned x, unsigned& nloc, unsigned& nx) {
;     const unsigned G = gridDim.x * gridDim.y * gridDim.z;
;     unsigned sum, cnt, mine, sp = 0u;
;     for (;;) {
;         sum = 0u; cnt = 0u; mine = 0u;
; #pragma unroll
;         for (unsigned j = 0; j < 16; ++j) { const unsigned c = xb_ld(&bar[XB_XCNT(j)]); sum += c; cnt += (c > 0u) ? 1u : 0u; mine = (j == x) ? c : mine; }
;         if (sum == G) break;
;         __builtin_amdgcn_s_sleep(1);
;         if ((++sp & 255u) == 0u) { if (xb_ld(&bar[XB_TMO])) break; if (sp > XB_SPIN_CAP) { atomicAdd(&bar[XB_TMO], 1u); break; } }
;     }
;     nloc = mine > 0u ? mine : 1u; nx = cnt > 0u ? cnt : 1u;
; }
; __global__ void __launch_bounds__(NTHREADS, 2) fwd_megakernel(Args args) {
;     ...
;     float* part = (float*)(ws + WS_PART); float* logf_ = (float*)(ws + WS_LOGF); float* cb = (float*)(ws + WS_CB);
;     int* jtab = (int*)(ws + WS_LOGF + 768 * 1024); float* wf_tab = (float*)(ws + WS_CB + 512 * 1024);
;     bf16_t* XB = (bf16_t*)(ws + WS_XB); bf16_t* QKV = (bf16_t*)(ws + WS_QKV); bf16_t* OB = (bf16_t*)(ws + WS_O); bf16_t* HB = (bf16_t*)(ws + WS_H);
.LBB0_38:
	v_writelane_b32 v252, s56, 16
	s_nop 1
	v_writelane_b32 v252, s57, 17
	v_writelane_b32 v252, s58, 18
	v_writelane_b32 v252, s59, 19
	v_writelane_b32 v252, s60, 20
	v_writelane_b32 v252, s61, 21
	v_writelane_b32 v252, s62, 22
	v_writelane_b32 v252, s63, 23
	v_writelane_b32 v252, s64, 24
	v_writelane_b32 v252, s65, 25
	v_writelane_b32 v252, s66, 26
	v_writelane_b32 v252, s67, 27
	v_writelane_b32 v252, s68, 28
	v_writelane_b32 v252, s69, 29
	v_writelane_b32 v252, s70, 30
	v_writelane_b32 v252, s71, 31
	s_or_b64 exec, exec, s[4:5]
	s_add_u32 s94, s84, 0x100000
	s_addc_u32 s95, s85, 0
	s_add_u32 s24, s84, 0x200000
	s_addc_u32 s25, s85, 0
	s_add_u32 s36, s84, 0x300000
	s_addc_u32 s69, s85, 0
	s_add_u32 s38, s84, 0x2c0000
	s_addc_u32 s39, s85, 0
	s_add_u32 s4, s84, 0x24c00000
	s_addc_u32 s5, s85, 0
	s_add_u32 s93, s84, 0x2400000
	s_addc_u32 s68, s85, 0
	s_add_u32 s26, s84, 0x27000000
	s_addc_u32 s27, s85, 0
	s_add_u32 s8, s84, 0xa400000
	s_addc_u32 s9, s85, 0
	v_readlane_b32 s23, v252, 10
	s_cmpk_lt_i32 s23, 0x400
	s_cselect_b64 s[6:7], -1, 0
	v_writelane_b32 v252, s6, 32
	s_lshr_b32 s1, s23, 8
	s_add_i32 s1, s1, s23
	v_writelane_b32 v252, s7, 33
	s_lshl_b32 s1, s1, 9
	v_readlane_b32 s3, v252, 15
	s_andn2_b32 s3, s3, 31
	s_and_b32 s1, s1, 0x600
	s_add_i32 s3, s3, -15
	v_writelane_b32 v252, s3, 34
	s_lshl_b32 s3, s1, 1
	s_add_u32 s6, s4, s3
	s_addc_u32 s7, s5, 0
	s_add_u32 s56, s84, 0x200
	s_addc_u32 s57, s85, 0
	s_add_u32 s14, s84, 0x1000
	s_addc_u32 s15, s85, 0
	s_add_u32 s16, s84, 0x1100
	s_addc_u32 s17, s85, 0
	s_add_u32 s18, s84, 0x1200
	s_addc_u32 s19, s85, 0
	s_add_u32 s20, s84, 0x1300
	s_addc_u32 s21, s85, 0
	v_writelane_b32 v252, s6, 35
	s_cmp_eq_u32 s0, 15
	v_mov_b32_e32 v139, 0
	v_writelane_b32 v252, s7, 36
	s_cselect_b64 s[6:7], -1, 0
	v_writelane_b32 v252, s6, 37
	s_cmp_eq_u32 s0, 14
	v_mov_b32_e32 v237, 0x358637bd
	v_writelane_b32 v252, s7, 38
	s_cselect_b64 s[6:7], -1, 0
	v_writelane_b32 v252, s6, 39
	s_cmp_eq_u32 s0, 13
	v_mov_b64_e32 v[192:193], 0xff
	v_writelane_b32 v252, s7, 40
	s_cselect_b64 s[6:7], -1, 0
	v_writelane_b32 v252, s6, 41
	s_cmp_eq_u32 s0, 12
	v_mov_b64_e32 v[194:195], 0x100
	v_writelane_b32 v252, s7, 42
	s_cselect_b64 s[6:7], -1, 0
	v_writelane_b32 v252, s6, 43
	s_cmp_eq_u32 s0, 11
	v_mbcnt_hi_u32_b32 v239, -1, v8
	v_writelane_b32 v252, s7, 44
	s_cselect_b64 s[6:7], -1, 0
	v_writelane_b32 v252, s6, 45
	s_cmp_eq_u32 s0, 10
	v_mov_b32_e32 v240, 0x7f800000
	v_writelane_b32 v252, s7, 46
	s_cselect_b64 s[6:7], -1, 0
	v_writelane_b32 v252, s6, 47
	s_cmp_eq_u32 s0, 9
	v_mov_b32_e32 v196, 0x3f317218
	v_writelane_b32 v252, s7, 48
	s_cselect_b64 s[6:7], -1, 0
	v_writelane_b32 v252, s6, 49
	s_cmp_eq_u32 s0, 8
	v_mov_b32_e32 v241, 0xff800000
	v_writelane_b32 v252, s7, 50
	s_cselect_b64 s[6:7], -1, 0
	v_writelane_b32 v252, s6, 51
	s_cmp_eq_u32 s0, 7
	v_mov_b32_e32 v238, 0xf149f2ca
	v_writelane_b32 v252, s7, 52
	s_cselect_b64 s[6:7], -1, 0
	v_writelane_b32 v252, s6, 53
	s_cmp_eq_u32 s0, 6
	v_mov_b64_e32 v[202:203], 0x580
	v_writelane_b32 v252, s7, 54
	s_cselect_b64 s[6:7], -1, 0
	v_writelane_b32 v252, s6, 55
	s_cmp_eq_u32 s0, 5
	v_mov_b64_e32 v[204:205], 0x57f
	v_writelane_b32 v252, s7, 56
	s_cselect_b64 s[6:7], -1, 0
	v_writelane_b32 v252, s6, 57
	s_cmp_eq_u32 s0, 4
	s_movk_i32 s66, 0x1080
	v_writelane_b32 v252, s7, 58
	s_cselect_b64 s[6:7], -1, 0
	v_writelane_b32 v252, s6, 59
	s_cmp_eq_u32 s0, 3
	s_movk_i32 s60, 0x2000
	v_writelane_b32 v252, s7, 60
	s_cselect_b64 s[6:7], -1, 0
	v_writelane_b32 v252, s6, 61
	s_cmp_eq_u32 s0, 2
	s_movk_i32 s62, 0x6000
	v_writelane_b32 v252, s7, 62
	s_cselect_b64 s[6:7], -1, 0
	v_writelane_b32 v252, s6, 63
	s_cmp_eq_u32 s0, 1
	s_mov_b32 s64, 0xa000
	v_writelane_b32 v254, s7, 0
	s_cselect_b64 s[6:7], -1, 0
	v_writelane_b32 v254, s6, 1
	s_cmp_eq_u32 s0, 0
	s_mov_b32 s67, 0xc000
	v_writelane_b32 v254, s7, 2
	s_cselect_b64 s[6:7], -1, 0
	s_lshl_b32 s0, s0, 8
	s_add_u32 s0, s84, s0
	v_writelane_b32 v254, s6, 3
	s_addc_u32 s3, s85, 0
	s_mov_b32 s65, 0x24c00000
	v_writelane_b32 v254, s7, 4
	s_add_u32 s6, s0, 0x1400
	s_addc_u32 s7, s3, 0
	s_add_u32 s58, s0, 0x2400
	v_writelane_b32 v254, s6, 5
	s_addc_u32 s59, s3, 0
	s_mov_b32 s89, 0x42800000
	v_writelane_b32 v254, s7, 6
	s_add_u32 s6, s84, 0x3400
	s_addc_u32 s7, s85, 0
	s_add_u32 s72, s84, 0x3500
	v_writelane_b32 v254, s6, 7
	s_addc_u32 s73, s85, 0
	s_add_u32 s0, s84, 0x14000000
	v_writelane_b32 v254, s7, 8
	v_writelane_b32 v254, s0, 9
	s_addc_u32 s0, s85, 0
	s_ashr_i32 s3, s2, 31
	s_cmpk_lt_i32 s2, 0x100
	v_writelane_b32 v254, s0, 10
	s_cselect_b64 s[6:7], -1, 0
	s_lshr_b32 s0, s3, 29
	v_writelane_b32 v254, s6, 11
	s_add_i32 s0, s2, s0
	s_ashr_i32 s88, s33, 31
	v_writelane_b32 v254, s7, 12
	s_ashr_i32 s6, s0, 3
	s_and_b32 s0, s0, -8
	s_sub_i32 s0, s2, s0
	s_lshl_b32 s7, s0, 5
	s_add_u32 s10, s84, 0x10000000
	v_writelane_b32 v254, s10, 13
	s_addc_u32 s10, s85, 0
	s_cmpk_lt_i32 s2, 0x300
	v_writelane_b32 v254, s10, 14
	s_cselect_b64 s[10:11], -1, 0
	v_writelane_b32 v254, s10, 15
	s_cmp_lt_i32 s0, 0
	s_movk_i32 s97, 0x2c00
	v_writelane_b32 v254, s11, 16
	s_mul_i32 s10, s0, 33
	s_cselect_b32 s7, s10, s7
	s_movk_i32 s10, 0x61
	s_cselect_b32 s10, s10, 0x60
	s_mul_i32 s10, s10, s0
	s_movk_i32 s11, 0xb1
	s_cselect_b32 s12, s11, 0xb0
	s_add_i32 s10, s10, s6
	s_mul_hi_i32 s11, s10, 0x2aaaaaab
	s_lshr_b32 s13, s11, 31
	s_ashr_i32 s11, s11, 5
	s_add_i32 s11, s11, s13
	s_mul_i32 s13, s11, 0xc0
	s_sub_i32 s10, s10, s13
	s_bfe_u32 s13, s10, 0x3001c
	s_add_i32 s13, s10, s13
	s_and_b32 s22, s13, 0xfff8
	s_sub_i32 s10, s10, s22
	s_lshl_b32 s11, s11, 3
	s_sext_i32_i16 s10, s10
	s_add_i32 s28, s11, s10
	s_sext_i32_i16 s10, s13
	s_ashr_i32 s29, s10, 3
	s_cmp_gt_i32 s2, 15
	s_cselect_b64 s[10:11], -1, 0
	v_writelane_b32 v254, s10, 17
	s_mul_i32 s0, s12, s0
	s_mov_b64 s[90:91], 0
	v_writelane_b32 v254, s11, 18
	v_readlane_b32 s10, v252, 13
	s_addk_i32 s10, 0xff80
	v_readlane_b32 s11, v252, 14
	v_writelane_b32 v254, s10, 19
	s_lshl_b32 s10, s2, 3
	v_writelane_b32 v254, s10, 20
	s_addk_i32 s10, 0xff80
	v_writelane_b32 v254, s10, 21
	s_add_u32 s10, s84, 0x13000000
	v_writelane_b32 v254, s10, 22
	s_addc_u32 s10, s85, 0
	s_cmp_lt_i32 s2, 16
	v_writelane_b32 v254, s10, 23
	s_cselect_b64 s[10:11], -1, 0
	v_writelane_b32 v254, s10, 24
	s_barrier
;     __device__ bool next(int i, Unit& u) const {
;         const long L = (long)i * G + c; if (L >= nwg) return false;
;         int wgid = (int)L; { const int q = nwg / NXCD, r = nwg % NXCD, xcd = wgid % NXCD, off = wgid / NXCD; wgid = (xcd < r ? xcd * (q + 1) : r * (q + 1) + (xcd - r) * q) + off; }
;         const int nig = WGM * nN, gid = wgid / nig, fm = gid * WGM, gsz = (nM - fm) < WGM ? (nM - fm) : WGM;
;         u.pm = fm + ((wgid % nig) % gsz); u.pn = (wgid % nig) / gsz; return true;
;     }
	s_nop 0
	v_writelane_b32 v254, s11, 25
	s_lshl_b64 s[10:11], s[2:3], 15
	s_add_u32 s30, s24, s10
	v_writelane_b32 v254, s24, 26
	s_addc_u32 s31, s25, s11
	s_add_u32 s10, s36, s10
	v_writelane_b32 v254, s25, 27
	v_writelane_b32 v254, s30, 28
	s_addc_u32 s11, s69, s11
	s_nop 0
	v_writelane_b32 v254, s31, 29
	v_writelane_b32 v254, s10, 30
	s_mov_b32 s31, 0
	s_nop 0
	v_writelane_b32 v254, s11, 31
	s_lshl_b32 s10, s2, 5
	s_add_u32 s24, s84, 0x4400000
	s_addc_u32 s25, s85, 0
	s_add_u32 s34, s84, 0x6400000
	s_addc_u32 s35, s85, 0
	v_writelane_b32 v254, s10, 32
	s_add_u32 s10, s84, 0x3800
	v_writelane_b32 v254, s10, 33
	s_addc_u32 s10, s85, 0
	s_cmpk_lt_i32 s23, 0x200
	v_writelane_b32 v254, s10, 34
	s_cselect_b64 s[10:11], -1, 0
	v_writelane_b32 v254, s10, 35
	s_and_b32 s13, s23, 15
	s_lshl_b32 s22, s13, 21
	v_writelane_b32 v254, s11, 36
	s_ashr_i32 s10, s23, 4
	s_sub_i32 s30, 31, s10
	s_lshl_b64 s[10:11], s[30:31], 16
	s_add_u32 s10, s93, s10
	s_addc_u32 s11, s68, s11
	s_add_u32 s10, s10, s22
	s_addc_u32 s11, s11, 0
	v_writelane_b32 v254, s10, 37
	s_nop 1
	v_writelane_b32 v254, s11, 38
	v_writelane_b32 v254, s24, 39
	s_add_u32 s10, s24, s22
	v_writelane_b32 v254, s25, 40
	s_addc_u32 s11, s25, 0
	v_writelane_b32 v254, s10, 41
	s_nop 1
	v_writelane_b32 v254, s11, 42
	v_writelane_b32 v254, s34, 43
	s_add_u32 s10, s34, s22
	v_writelane_b32 v254, s35, 44
	s_addc_u32 s11, s35, 0
	v_writelane_b32 v254, s10, 45
	s_movk_i32 s34, 0x1000
	s_movk_i32 s35, 0xdfff
	v_writelane_b32 v254, s11, 46
	s_lshl_b32 s10, s13, 15
	s_add_u32 s10, s36, s10
	v_writelane_b32 v254, s36, 47
	s_addc_u32 s11, s69, 0
	v_writelane_b32 v254, s10, 48
	s_nop 1
	v_writelane_b32 v254, s11, 49
	s_mul_i32 s10, s30, 0x108000
	s_add_u32 s10, s26, s10
	s_mul_hi_u32 s11, s30, 0x108000
	s_addc_u32 s11, s27, s11
	s_lshl_b32 s22, s13, 8
	s_add_u32 s10, s10, s22
	s_addc_u32 s11, s11, 0
	v_writelane_b32 v254, s10, 50
	s_nop 1
	v_writelane_b32 v254, s11, 51
	s_lshl_b32 s10, s13, 5
	s_lshl_b32 s11, s30, 8
	s_add_i32 s30, s10, s30
	v_writelane_b32 v254, s11, 52
	s_lshl_b64 s[10:11], s[30:31], 2
	s_add_u32 s10, s38, s10
	v_writelane_b32 v254, s38, 53
	s_addc_u32 s11, s39, s11
	s_cmpk_lt_i32 s2, 0x580
	v_writelane_b32 v254, s39, 54
	v_writelane_b32 v254, s10, 55
	v_readlane_b32 s36, v252, 0
	v_readlane_b32 s42, v252, 6
	v_writelane_b32 v254, s11, 56
	s_cselect_b64 s[10:11], -1, 0
	v_writelane_b32 v254, s10, 57
	s_add_i32 s0, s0, s6
	v_readlane_b32 s37, v252, 1
	v_writelane_b32 v254, s11, 58
	s_mul_hi_i32 s10, s0, 0x2e8ba2e9
	s_lshr_b32 s11, s10, 31
	s_ashr_i32 s10, s10, 6
	s_add_i32 s10, s10, s11
	s_mul_i32 s11, s10, 0x160
	s_sub_i32 s0, s0, s11
	s_bfe_u32 s11, s0, 0x3001c
	s_add_i32 s11, s0, s11
	s_and_b32 s12, s11, 0xfff8
	s_sub_i32 s0, s0, s12
	s_lshl_b32 s10, s10, 3
	s_sext_i32_i16 s0, s0
	s_add_i32 s10, s10, s0
	s_sext_i32_i16 s0, s11
	s_ashr_i32 s0, s0, 3
	v_writelane_b32 v254, s0, 59
	s_and_b32 s30, s0, 0x7fffffff
	s_lshl_b32 s0, s10, 8
	v_writelane_b32 v254, s0, 60
	s_mul_hi_i32 s0, s10, 0x108000
	v_writelane_b32 v254, s10, 61
	s_mul_i32 s10, s10, 0x108000
	s_lshl_b64 s[12:13], s[30:31], 14
	s_add_u32 s10, s4, s10
	v_writelane_b32 v254, s12, 62
	s_addc_u32 s11, s5, s0
	v_readlane_b32 s38, v252, 2
	v_writelane_b32 v254, s13, 63
	s_add_u32 s12, s10, 0x84000
	v_writelane_b32 v255, s10, 0
	s_addc_u32 s13, s11, 0
	v_readlane_b32 s39, v252, 3
	v_writelane_b32 v255, s11, 1
	v_writelane_b32 v255, s12, 2
	v_readlane_b32 s40, v252, 4
	v_readlane_b32 s41, v252, 5
	v_writelane_b32 v255, s13, 3
	v_readlane_b32 s43, v252, 7
	s_add_u32 s0, s42, 0xb000000
	v_writelane_b32 v255, s0, 4
	s_addc_u32 s0, s43, 0
	v_readlane_b32 s36, v252, 16
	v_readlane_b32 s40, v252, 20
	v_readlane_b32 s41, v252, 21
	s_add_u32 s10, s40, 0x4000
	v_writelane_b32 v255, s0, 5
	s_addc_u32 s11, s41, 0
	v_writelane_b32 v255, s10, 6
	v_readlane_b32 s37, v252, 17
	s_mov_b64 s[36:37], 0x80
	v_writelane_b32 v255, s11, 7
	s_add_u32 s10, s84, 0x19c00000
	s_addc_u32 s11, s85, 0
	v_writelane_b32 v255, s10, 8
	s_add_u32 s0, s84, 0x1f400000
	v_readlane_b32 s38, v252, 18
	v_writelane_b32 v255, s11, 9
	v_writelane_b32 v255, s0, 10
	s_addc_u32 s0, s85, 0
	v_writelane_b32 v255, s0, 11
	s_add_i32 s0, s7, s6
	s_ashr_i32 s6, s0, 31
	s_lshr_b32 s6, s6, 26
	s_add_i32 s6, s0, s6
	s_and_b32 s7, s6, 0xffc0
	s_sub_i32 s0, s0, s7
	s_bfe_i32 s7, s0, 0x80000
	s_bfe_u32 s7, s7, 0x3000c
	s_add_i32 s7, s0, s7
	s_and_b32 s10, s7, 0xf8
	s_sub_i32 s0, s0, s10
	s_ashr_i32 s6, s6, 6
	s_lshl_b32 s6, s6, 3
	s_sext_i32_i8 s0, s0
	s_add_i32 s22, s6, s0
	v_writelane_b32 v255, s29, 12
	s_lshl_b32 s6, s28, 8
	s_bfe_i32 s0, s7, 0x80000
	s_and_b32 s30, s29, 0x7fffffff
	v_writelane_b32 v255, s6, 13
	s_sext_i32_i16 s0, s0
;     __device__ bool next(int i, Unit& u) const {
;         const long L = (long)i * G + c; if (L >= nwg) return false;
;         int wgid = (int)L; { const int q = nwg / NXCD, r = nwg % NXCD, xcd = wgid % NXCD, off = wgid / NXCD; wgid = (xcd < r ? xcd * (q + 1) : r * (q + 1) + (xcd - r) * q) + off; }
;         const int nig = WGM * nN, gid = wgid / nig, fm = gid * WGM, gsz = (nM - fm) < WGM ? (nM - fm) : WGM;
;         u.pm = fm + ((wgid % nig) % gsz); u.pn = (wgid % nig) / gsz; return true;
;     }
; __global__ void __launch_bounds__(NTHREADS, 2) fwd_megakernel(Args args) {
;     ...
;                 const int rem = ((S / 256) * (2 * FF / 256)) % G, nidle = rem ? G - rem : G, idx = rem ? bx - rem : bx;
;                 if (idx >= 0) {
;                     constexpr int L2_ITEMS = 1536 + 2816, L2_CUT = L2_ITEMS - 940;
;                     if (layer + 1 < NLAYER) CONV_LAYER(layer + 1, idx * 8 + wid, nidle * 8, 0, (layer == 1 ? L2_CUT : 0x7fffffff), 3);
;                     if (layer == 0) CONV_LAYER(2, idx * 8 + wid, nidle * 8, L2_CUT, 0x7fffffff, 3);
;                     CONV_LAYER(layer, nidle * 8 - 1 - (idx * 8 + wid), nidle * 8, 0, 0x7fffffff, 4);
	v_writelane_b32 v255, s28, 14
	s_lshl_b64 s[10:11], s[30:31], 14
	s_ashr_i32 s24, s0, 3
	s_mul_i32 s7, s28, 0x108000
	v_writelane_b32 v255, s10, 15
	s_mul_hi_i32 s6, s28, 0x108000
	v_readlane_b32 s39, v252, 19
	v_writelane_b32 v255, s11, 16
	s_add_u32 s10, s4, s7
	s_addc_u32 s11, s5, s6
	s_add_u32 s6, s10, 0x84000
	v_writelane_b32 v255, s10, 17
	s_addc_u32 s7, s11, 0
	v_readlane_b32 s42, v252, 22
	v_writelane_b32 v255, s11, 18
	s_ashr_i32 s10, s0, 4
	v_writelane_b32 v255, s6, 19
	s_ashr_i32 s11, s10, 31
	s_lshl_b32 s0, s24, 14
	v_writelane_b32 v255, s7, 20
	s_lshl_b64 s[6:7], s[10:11], 19
	v_writelane_b32 v255, s6, 21
	s_lshl_b64 s[12:13], s[10:11], 10
	s_and_b32 s0, s0, 0x4000
	v_writelane_b32 v255, s7, 22
	s_mul_i32 s6, s22, 0x108000
	v_writelane_b32 v255, s0, 23
	s_mul_hi_i32 s0, s22, 0x108000
	s_add_u32 s6, s26, s6
	v_writelane_b32 v255, s26, 24
	s_addc_u32 s7, s27, s0
	s_add_u32 s10, s6, s12
	v_writelane_b32 v255, s27, 25
	s_addc_u32 s11, s7, s13
	s_add_u32 s12, s10, 0x84000
	v_writelane_b32 v255, s10, 26
	s_addc_u32 s13, s11, 0
	s_and_b32 s30, s24, 0x7fffffff
	v_writelane_b32 v255, s11, 27
	v_writelane_b32 v255, s12, 28
	s_lshl_b64 s[10:11], s[30:31], 14
	s_mul_hi_i32 s0, s22, 0x2c0000
	v_writelane_b32 v255, s13, 29
	v_writelane_b32 v255, s24, 30
	v_writelane_b32 v255, s10, 31
	v_readlane_b32 s43, v252, 23
	v_readlane_b32 s44, v252, 24
	v_writelane_b32 v255, s11, 32
	s_add_u32 s10, s6, 0x84000
	v_writelane_b32 v255, s6, 33
	s_addc_u32 s11, s7, 0
	v_readlane_b32 s45, v252, 25
	v_writelane_b32 v255, s7, 34
	s_mul_i32 s6, s22, 0x2c0000
	v_writelane_b32 v255, s10, 35
	s_add_u32 s6, s8, s6
	s_addc_u32 s7, s9, s0
	v_writelane_b32 v255, s11, 36
	v_writelane_b32 v255, s22, 37
	s_add_u32 s10, s6, 0x160000
	v_writelane_b32 v255, s6, 38
	s_addc_u32 s11, s7, 0
	s_abs_i32 s0, s33
	v_cvt_f32_u32_e32 v0, s0
	v_writelane_b32 v255, s7, 39
	s_sub_i32 s6, 0, s0
	v_writelane_b32 v255, s10, 40
	v_rcp_iflag_f32_e32 v0, v0
	v_readlane_b32 s46, v252, 26
	v_writelane_b32 v255, s11, 41
	v_readlane_b32 s47, v252, 27
	v_mul_f32_e32 v0, 0x4f7ffffe, v0
	v_cvt_u32_f32_e32 v0, v0
	v_readlane_b32 s48, v252, 28
	v_readlane_b32 s49, v252, 29
	v_readlane_b32 s50, v252, 30
	v_readfirstlane_b32 s7, v0
	s_mul_i32 s6, s6, s7
	s_mul_hi_u32 s6, s7, s6
	s_add_i32 s7, s7, s6
	s_mul_hi_u32 s6, s7, 0x580
	s_mul_i32 s6, s6, s0
	s_sub_i32 s6, 0x580, s6
	s_sub_i32 s7, s6, s0
	s_cmp_ge_u32 s6, s0
	s_cselect_b32 s6, s7, s6
	s_sub_i32 s7, s6, s0
	s_cmp_ge_u32 s6, s0
	s_cselect_b32 s0, s7, s6
	s_sub_i32 s6, s2, s0
	s_cmp_gt_i32 s6, -1
	s_cselect_b64 s[10:11], -1, 0
	s_sub_i32 s7, s33, s0
	v_writelane_b32 v255, s10, 42
	s_lshl_b32 s61, s7, 3
	s_lshl_b32 s6, s6, 3
	v_writelane_b32 v255, s11, 43
	s_max_u32 s10, s61, 1
	v_cvt_f32_u32_e32 v0, s10
	v_writelane_b32 v255, s10, 44
	s_sub_i32 s10, 0, s10
	s_lshl_b32 s96, s33, 5
	v_rcp_iflag_f32_e32 v0, v0
	v_readlane_b32 s51, v252, 31
	v_mul_f32_e32 v0, 0x4f7ffffe, v0
	v_cvt_u32_f32_e32 v0, v0
	s_nop 0
	v_readfirstlane_b32 s11, v0
	s_mul_i32 s10, s10, s11
	s_mul_hi_u32 s10, s11, s10
	s_add_i32 s10, s11, s10
	v_writelane_b32 v255, s10, 45
	s_lshl_b32 s10, s33, 10
	s_lshl_b32 s11, s0, 10
	s_sub_i32 s10, s10, s11
	v_writelane_b32 v255, s10, 46
	v_writelane_b32 v255, s6, 47
	s_lshl_b32 s6, s0, 3
	v_writelane_b32 v255, s6, 48
	s_lshl_b32 s0, s0, 11
	s_lshl_b32 s6, s33, 11
	s_lshl_b32 s10, s2, 10
	s_sub_i32 s63, s6, s0
	s_lshl_b32 s0, s2, 11
	s_sub_i32 s10, s10, s11
	s_add_i32 s11, s0, 0xffff8000
	v_writelane_b32 v255, s11, 49
	s_sub_i32 s0, s6, s0
	s_addk_i32 s6, 0x8000
	v_writelane_b32 v255, s6, 50
	s_add_i32 s6, s10, 0xfffd0000
	v_writelane_b32 v255, s6, 51
	s_lshl_b32 s6, s7, 10
	v_writelane_b32 v255, s6, 52
	s_addk_i32 s0, 0xff00
	v_writelane_b32 v255, s0, 53
	s_lshl_b32 s0, s1, 2
	v_writelane_b32 v255, s0, 54
	s_lshl_b32 s0, s23, 5
	s_or_b32 s1, s0, 3
	v_writelane_b32 v255, s1, 55
	s_or_b32 s1, s0, 2
	v_writelane_b32 v255, s1, 56
	v_writelane_b32 v255, s0, 57
	s_or_b32 s0, s0, 1
	v_writelane_b32 v255, s0, 58
	s_add_i32 s0, 0, 0x17800
	v_writelane_b32 v255, s0, 59
	s_add_i32 s0, 0, 0x17838
	v_writelane_b32 v255, s0, 60
	s_add_i32 s0, 0, 0x7000
	v_writelane_b32 v255, s0, 61
	s_add_i32 s0, 0, 0x23ff0
	v_writelane_b32 v255, s0, 62
	s_add_i32 s0, 0, 0x23ff4
	v_writelane_b32 v255, s0, 63
	s_add_i32 s0, 0, 0x20800
	v_writelane_b32 v253, s0, 0
	s_add_i32 s0, 0, 0x23fe0
	v_writelane_b32 v253, s0, 1
	v_writelane_b32 v253, s68, 2
	v_writelane_b32 v253, s56, 3
	s_mov_b32 s11, 0xe000
	s_mov_b32 s10, 0xbfb8aa3b
	v_writelane_b32 v253, s57, 4
	v_writelane_b32 v253, s58, 5
	s_nop 1
	v_writelane_b32 v253, s59, 6
	v_writelane_b32 v253, s72, 7
	s_nop 1
	v_writelane_b32 v253, s73, 8
	s_mov_b64 s[22:23], 0
	s_branch .LBB0_980
